# attention row-max: cross-half exchange via v_permlane32_swap instead of ds_bpermute + LDS wait (32 sites)
# baseline (speedup 1.0000x reference)
.LBB0_206:
	s_mul_i32 s2, s38, 0x5000
	v_lshl_or_b32 v0, v209, 1, s2
	v_lshl_add_u32 v220, v218, 1, v0
	ds_read_b128 v[4:7], v220
	v_lshl_add_u32 v14, v217, 1, v0
	ds_read_b128 v[8:11], v14
	v_lshl_add_u32 v221, v216, 1, v0
	v_lshl_add_u32 v13, v215, 1, v0
	v_or_b32_e32 v219, s2, v209
	v_lshl_add_u32 v15, v214, 1, v219
	v_lshl_add_u32 v12, v213, 1, v219
	v_cmp_lt_i32_e32 vcc, v180, v182
	s_waitcnt lgkmcnt(0)
	v_mfma_f32_32x32x16_bf16 v[96:111], v[4:7], v[152:155], 0
	ds_read_b128 v[222:225], v12 offset:16384
	v_cndmask_b32_e32 v0, v179, v180, vcc
	v_lshlrev_b32_e32 v0, 2, v0
	v_mfma_f32_32x32x16_bf16 v[80:95], v[4:7], v[156:159], 0
	ds_read_b128 v[4:7], v221
	v_mfma_f32_32x32x16_bf16 v[96:111], v[8:11], v[140:143], v[96:111]
	v_mfma_f32_32x32x16_bf16 v[80:95], v[8:11], v[148:151], v[80:95]
	ds_read_b128 v[8:11], v13
	s_waitcnt lgkmcnt(0)
	v_mfma_f32_32x32x16_bf16 v[96:111], v[4:7], v[136:139], v[96:111]
	v_mfma_f32_32x32x16_bf16 v[80:95], v[4:7], v[144:147], v[80:95]
	ds_read_b128 v[4:7], v15 offset:16384
	v_mfma_f32_32x32x16_bf16 v[96:111], v[8:11], v[124:127], v[96:111]
	s_waitcnt lgkmcnt(0)
	v_mfma_f32_32x32x16_bf16 v[96:111], v[4:7], v[120:123], v[96:111]
	v_mfma_f32_32x32x16_bf16 v[96:111], v[222:225], v[112:115], v[96:111]
	v_mfma_f32_32x32x16_bf16 v[80:95], v[8:11], v[132:135], v[80:95]
	s_nop 10
	v_max_f32_e32 v188, v97, v97
	v_max_f32_e32 v8, v96, v96
	v_max_f32_e32 v8, v8, v188
	v_max3_f32 v8, v8, v98, v99
	v_max3_f32 v8, v8, v100, v101
	v_max3_f32 v8, v8, v102, v103
	v_max3_f32 v8, v8, v104, v105
	v_mfma_f32_32x32x16_bf16 v[80:95], v[4:7], v[128:131], v[80:95]
	v_max3_f32 v8, v8, v106, v107
	v_max3_f32 v4, v8, v108, v109
	v_max3_f32 v4, v4, v110, v111
	v_mov_b32_e32 v5, v4
	s_nop 1
	v_permlane32_swap_b32_e32 v5, v4
	s_nop 1
	s_waitcnt lgkmcnt(0)
	v_max_f32_e32 v5, v5, v5
	v_mfma_f32_32x32x16_bf16 v[80:95], v[222:225], v[116:119], v[80:95]
	v_max_f32_e32 v4, v4, v5
	v_add_f32_e32 v5, 0x41000000, v1
	v_cmp_gt_f32_e32 vcc, v4, v5
	s_cbranch_vccz .LBB0_208
	v_max_f32_e32 v4, v4, v4
	v_max_f32_e32 v5, v1, v1
	v_max_f32_e32 v5, v5, v4
	v_sub_f32_e32 v1, v1, v5
	v_exp_f32_e32 v4, v1
	v_mov_b32_e32 v1, v5
	v_mul_f32_e32 v3, v3, v4
	v_pk_mul_f32 v[78:79], v[78:79], v[4:5] op_sel_hi:[1,0]
	v_pk_mul_f32 v[76:77], v[76:77], v[4:5] op_sel_hi:[1,0]
	v_pk_mul_f32 v[74:75], v[74:75], v[4:5] op_sel_hi:[1,0]
	v_pk_mul_f32 v[72:73], v[72:73], v[4:5] op_sel_hi:[1,0]
	v_pk_mul_f32 v[70:71], v[70:71], v[4:5] op_sel_hi:[1,0]
	v_pk_mul_f32 v[68:69], v[68:69], v[4:5] op_sel_hi:[1,0]
	v_pk_mul_f32 v[66:67], v[66:67], v[4:5] op_sel_hi:[1,0]
	v_pk_mul_f32 v[64:65], v[64:65], v[4:5] op_sel_hi:[1,0]
	v_pk_mul_f32 v[62:63], v[62:63], v[4:5] op_sel_hi:[1,0]
	v_pk_mul_f32 v[60:61], v[60:61], v[4:5] op_sel_hi:[1,0]
	v_pk_mul_f32 v[58:59], v[58:59], v[4:5] op_sel_hi:[1,0]
	v_pk_mul_f32 v[56:57], v[56:57], v[4:5] op_sel_hi:[1,0]
	v_pk_mul_f32 v[54:55], v[54:55], v[4:5] op_sel_hi:[1,0]
	v_pk_mul_f32 v[52:53], v[52:53], v[4:5] op_sel_hi:[1,0]
	v_pk_mul_f32 v[50:51], v[50:51], v[4:5] op_sel_hi:[1,0]
	v_pk_mul_f32 v[48:49], v[48:49], v[4:5] op_sel_hi:[1,0]
.LBB0_208:
	s_nop 7
	v_max_f32_e32 v4, v81, v81
	v_max_f32_e32 v5, v80, v80
	v_max_f32_e32 v4, v5, v4
	v_max3_f32 v4, v4, v82, v83
	v_max3_f32 v4, v4, v84, v85
	v_max3_f32 v4, v4, v86, v87
	v_max3_f32 v4, v4, v88, v89
	v_max3_f32 v4, v4, v90, v91
	v_max3_f32 v4, v4, v92, v93
	v_max3_f32 v4, v4, v94, v95
	v_mov_b32_e32 v5, v4
	s_nop 1
	v_permlane32_swap_b32_e32 v5, v4
	s_nop 1
	s_waitcnt lgkmcnt(0)
	v_max_f32_e32 v5, v5, v5
	v_max_f32_e32 v4, v4, v5
	v_add_f32_e32 v5, 0x41000000, v205
	v_cmp_gt_f32_e32 vcc, v4, v5
	s_cbranch_vccz .LBB0_210
	v_max_f32_e32 v4, v4, v4
	v_max_f32_e32 v5, v205, v205
	v_max_f32_e32 v5, v5, v4
	v_sub_f32_e32 v4, v205, v5
	v_exp_f32_e32 v4, v4
	v_mov_b32_e32 v205, v5
	v_mul_f32_e32 v208, v208, v4
	v_pk_mul_f32 v[46:47], v[46:47], v[4:5] op_sel_hi:[1,0]
	v_pk_mul_f32 v[44:45], v[44:45], v[4:5] op_sel_hi:[1,0]
	v_pk_mul_f32 v[42:43], v[42:43], v[4:5] op_sel_hi:[1,0]
	v_pk_mul_f32 v[40:41], v[40:41], v[4:5] op_sel_hi:[1,0]
	v_pk_mul_f32 v[38:39], v[38:39], v[4:5] op_sel_hi:[1,0]
	v_pk_mul_f32 v[36:37], v[36:37], v[4:5] op_sel_hi:[1,0]
	v_pk_mul_f32 v[34:35], v[34:35], v[4:5] op_sel_hi:[1,0]
	v_pk_mul_f32 v[32:33], v[32:33], v[4:5] op_sel_hi:[1,0]
	v_pk_mul_f32 v[30:31], v[30:31], v[4:5] op_sel_hi:[1,0]
	v_pk_mul_f32 v[28:29], v[28:29], v[4:5] op_sel_hi:[1,0]
	v_pk_mul_f32 v[26:27], v[26:27], v[4:5] op_sel_hi:[1,0]
	v_pk_mul_f32 v[24:25], v[24:25], v[4:5] op_sel_hi:[1,0]
	v_pk_mul_f32 v[22:23], v[22:23], v[4:5] op_sel_hi:[1,0]
	v_pk_mul_f32 v[20:21], v[20:21], v[4:5] op_sel_hi:[1,0]
	v_pk_mul_f32 v[18:19], v[18:19], v[4:5] op_sel_hi:[1,0]
	v_pk_mul_f32 v[16:17], v[16:17], v[4:5] op_sel_hi:[1,0]
.LBB0_210:
	v_sub_f32_e32 v4, v96, v1
	v_exp_f32_e32 v4, v4
	v_sub_f32_e32 v6, v97, v1
	v_exp_f32_e32 v6, v6
	v_sub_f32_e32 v7, v98, v1
	v_exp_f32_e32 v7, v7
	v_sub_f32_e32 v8, v99, v1
	v_exp_f32_e32 v8, v8
	v_add_f32_e32 v5, 0, v4
	v_add_f32_e32 v5, v6, v5
	v_add_f32_e32 v5, v7, v5
	v_add_f32_e32 v5, v8, v5
	v_cvt_pk_bf16_f32 v97, v7, v8
	v_sub_f32_e32 v8, v80, v205
	v_exp_f32_e32 v224, v8
	v_sub_f32_e32 v8, v81, v205
	v_exp_f32_e32 v226, v8
	v_sub_f32_e32 v8, v82, v205
	v_exp_f32_e32 v227, v8
	v_sub_f32_e32 v8, v83, v205
	v_exp_f32_e32 v228, v8
	v_sub_f32_e32 v8, v84, v205
	v_exp_f32_e32 v229, v8
	v_sub_f32_e32 v8, v85, v205
	v_exp_f32_e32 v230, v8
	v_sub_f32_e32 v8, v86, v205
	v_exp_f32_e32 v231, v8
	v_sub_f32_e32 v8, v87, v205
	v_exp_f32_e32 v232, v8
	v_sub_f32_e32 v8, v88, v205
	v_exp_f32_e32 v233, v8
	v_sub_f32_e32 v8, v89, v205
	v_add3_u32 v219, v219, v209, v160
	v_exp_f32_e32 v234, v8
	v_sub_f32_e32 v8, v90, v205
	v_lshl_add_u32 v84, v211, 1, v219
	v_lshl_add_u32 v88, v210, 1, v219
	v_exp_f32_e32 v235, v8
	v_sub_f32_e32 v8, v91, v205
	ds_read2st64_b64 v[84:87], v84 offset0:16 offset1:24
	ds_read2st64_b64 v[88:91], v88 offset0:16 offset1:24
	v_exp_f32_e32 v236, v8
	v_sub_f32_e32 v8, v92, v205
	v_sub_f32_e32 v9, v100, v1
	v_sub_f32_e32 v96, v103, v1
	v_exp_f32_e32 v237, v8
	v_sub_f32_e32 v8, v93, v205
	v_exp_f32_e32 v9, v9
	v_sub_f32_e32 v10, v101, v1
	v_exp_f32_e32 v99, v96
	v_sub_f32_e32 v96, v104, v1
	v_exp_f32_e32 v222, v8
	v_sub_f32_e32 v8, v94, v205
	v_exp_f32_e32 v10, v10
	v_sub_f32_e32 v11, v102, v1
	v_exp_f32_e32 v100, v96
	v_sub_f32_e32 v96, v105, v1
	v_exp_f32_e32 v223, v8
	v_sub_f32_e32 v8, v95, v205
	s_waitcnt lgkmcnt(0)
	v_mov_b32_e32 v92, v84
	v_mov_b32_e32 v93, v85
	v_mov_b32_e32 v94, v88
	v_mov_b32_e32 v95, v89
	v_mov_b32_e32 v88, v86
	v_mov_b32_e32 v89, v87
	v_exp_f32_e32 v11, v11
	v_exp_f32_e32 v101, v96
	v_sub_f32_e32 v96, v106, v1
	v_exp_f32_e32 v102, v96
	v_sub_f32_e32 v96, v107, v1
	v_add_f32_e32 v5, v9, v5
	v_exp_f32_e32 v103, v96
	v_sub_f32_e32 v96, v108, v1
	v_add_f32_e32 v5, v10, v5
	v_exp_f32_e32 v104, v96
	v_sub_f32_e32 v96, v109, v1
	v_cvt_pk_bf16_f32 v80, v224, v226
	v_cvt_pk_bf16_f32 v81, v227, v228
	v_cvt_pk_bf16_f32 v82, v229, v230
	v_cvt_pk_bf16_f32 v83, v231, v232
	v_add_f32_e32 v5, v11, v5
	v_exp_f32_e32 v105, v96
	v_sub_f32_e32 v96, v110, v1
	v_mfma_f32_32x32x16_bf16 v[32:47], v[92:95], v[80:83], v[32:47]
	v_lshl_add_u32 v84, v206, 1, v219
	v_add_f32_e32 v5, v99, v5
	v_exp_f32_e32 v106, v96
	v_sub_f32_e32 v96, v111, v1
	ds_read2st64_b64 v[84:87], v84 offset0:16 offset1:24
	v_add_f32_e32 v5, v100, v5
	v_exp_f32_e32 v107, v96
	v_mfma_f32_32x32x16_bf16 v[16:31], v[88:91], v[80:83], v[16:31]
	v_lshl_add_u32 v80, v207, 1, v219
	ds_read2st64_b64 v[80:83], v80 offset0:16 offset1:24
	v_cvt_pk_bf16_f32 v96, v4, v6
	v_cvt_pk_bf16_f32 v98, v9, v10
	v_cvt_pk_bf16_f32 v99, v11, v99
	v_add_f32_e32 v5, v101, v5
	v_add_f32_e32 v5, v102, v5
	v_mfma_f32_32x32x16_bf16 v[64:79], v[92:95], v[96:99], v[64:79]
	v_add_f32_e32 v5, v103, v5
	v_add_f32_e32 v5, v104, v5
	v_add_f32_e32 v5, v105, v5
	v_add_f32_e32 v5, v106, v5
	v_add_f32_e32 v5, v107, v5
	v_add_f32_e32 v3, v3, v5
	v_cvt_pk_bf16_f32 v4, v100, v101
	v_mfma_f32_32x32x16_bf16 v[48:63], v[88:91], v[96:99], v[48:63]
	s_waitcnt lgkmcnt(0)
	v_mov_b32_e32 v88, v80
	v_mov_b32_e32 v89, v81
	v_mov_b32_e32 v90, v84
	v_mov_b32_e32 v91, v85
	v_mov_b32_e32 v84, v82
	v_mov_b32_e32 v85, v83
	v_cvt_pk_bf16_f32 v5, v102, v103
	v_cvt_pk_bf16_f32 v6, v104, v105
	v_cvt_pk_bf16_f32 v7, v106, v107
	v_exp_f32_e32 v225, v8
	v_cvt_pk_bf16_f32 v8, v233, v234
	v_mfma_f32_32x32x16_bf16 v[64:79], v[88:91], v[4:7], v[64:79]
	v_cvt_pk_bf16_f32 v9, v235, v236
	v_cvt_pk_bf16_f32 v10, v237, v222
	v_cvt_pk_bf16_f32 v11, v223, v225
	v_mfma_f32_32x32x16_bf16 v[48:63], v[84:87], v[4:7], v[48:63]
	ds_read_b128 v[4:7], v220 offset:4096
	v_mfma_f32_32x32x16_bf16 v[32:47], v[88:91], v[8:11], v[32:47]
	v_mfma_f32_32x32x16_bf16 v[16:31], v[84:87], v[8:11], v[16:31]
	s_waitcnt lgkmcnt(0)
	v_mfma_f32_32x32x16_bf16 v[96:111], v[4:7], v[152:155], 0
	v_mfma_f32_32x32x16_bf16 v[80:95], v[4:7], v[156:159], 0
	ds_read_b128 v[4:7], v14 offset:4096
	s_waitcnt lgkmcnt(0)
	v_mfma_f32_32x32x16_bf16 v[96:111], v[4:7], v[140:143], v[96:111]
	v_mfma_f32_32x32x16_bf16 v[80:95], v[4:7], v[148:151], v[80:95]
	ds_read_b128 v[4:7], v221 offset:4096
	s_waitcnt lgkmcnt(0)
	v_mfma_f32_32x32x16_bf16 v[96:111], v[4:7], v[136:139], v[96:111]
	v_mfma_f32_32x32x16_bf16 v[80:95], v[4:7], v[144:147], v[80:95]
	ds_read_b128 v[4:7], v13 offset:4096
	s_waitcnt lgkmcnt(0)
	v_mfma_f32_32x32x16_bf16 v[96:111], v[4:7], v[124:127], v[96:111]
	v_mfma_f32_32x32x16_bf16 v[80:95], v[4:7], v[132:135], v[80:95]
	ds_read_b128 v[4:7], v15 offset:18432
	s_waitcnt lgkmcnt(0)
	v_mfma_f32_32x32x16_bf16 v[96:111], v[4:7], v[120:123], v[96:111]
	v_mfma_f32_32x32x16_bf16 v[80:95], v[4:7], v[128:131], v[80:95]
	ds_read_b128 v[4:7], v12 offset:18432
	s_waitcnt lgkmcnt(0)
	v_mfma_f32_32x32x16_bf16 v[96:111], v[4:7], v[112:115], v[96:111]
	v_mfma_f32_32x32x16_bf16 v[80:95], v[4:7], v[116:119], v[80:95]
	s_nop 10
	v_max_f32_e32 v4, v97, v97
	v_max_f32_e32 v5, v96, v96
	v_max_f32_e32 v4, v5, v4
	v_max3_f32 v4, v4, v98, v99
	v_max3_f32 v4, v4, v100, v101
	v_max3_f32 v4, v4, v102, v103
	v_max3_f32 v4, v4, v104, v105
	v_max3_f32 v4, v4, v106, v107
	v_max3_f32 v4, v4, v108, v109
	v_max3_f32 v4, v4, v110, v111
	v_mov_b32_e32 v5, v4
	s_nop 1
	v_permlane32_swap_b32_e32 v5, v4
	s_nop 1
	s_waitcnt lgkmcnt(0)
	v_max_f32_e32 v5, v5, v5
	v_max_f32_e32 v4, v4, v5
	v_add_f32_e32 v5, 0x41000000, v1
	v_cmp_gt_f32_e32 vcc, v4, v5
	s_cbranch_vccz .LBB0_212
	v_max_f32_e32 v4, v4, v4
	v_max_f32_e32 v5, v1, v1
	v_max_f32_e32 v5, v5, v4
	v_sub_f32_e32 v1, v1, v5
	v_exp_f32_e32 v4, v1
	v_mov_b32_e32 v1, v5
	v_mul_f32_e32 v3, v3, v4
	v_pk_mul_f32 v[78:79], v[78:79], v[4:5] op_sel_hi:[1,0]
	v_pk_mul_f32 v[76:77], v[76:77], v[4:5] op_sel_hi:[1,0]
	v_pk_mul_f32 v[74:75], v[74:75], v[4:5] op_sel_hi:[1,0]
	v_pk_mul_f32 v[72:73], v[72:73], v[4:5] op_sel_hi:[1,0]
	v_pk_mul_f32 v[70:71], v[70:71], v[4:5] op_sel_hi:[1,0]
	v_pk_mul_f32 v[68:69], v[68:69], v[4:5] op_sel_hi:[1,0]
	v_pk_mul_f32 v[66:67], v[66:67], v[4:5] op_sel_hi:[1,0]
	v_pk_mul_f32 v[64:65], v[64:65], v[4:5] op_sel_hi:[1,0]
	v_pk_mul_f32 v[62:63], v[62:63], v[4:5] op_sel_hi:[1,0]
	v_pk_mul_f32 v[60:61], v[60:61], v[4:5] op_sel_hi:[1,0]
	v_pk_mul_f32 v[58:59], v[58:59], v[4:5] op_sel_hi:[1,0]
	v_pk_mul_f32 v[56:57], v[56:57], v[4:5] op_sel_hi:[1,0]
	v_pk_mul_f32 v[54:55], v[54:55], v[4:5] op_sel_hi:[1,0]
	v_pk_mul_f32 v[52:53], v[52:53], v[4:5] op_sel_hi:[1,0]
	v_pk_mul_f32 v[50:51], v[50:51], v[4:5] op_sel_hi:[1,0]
	v_pk_mul_f32 v[48:49], v[48:49], v[4:5] op_sel_hi:[1,0]
.LBB0_212:
	v_add_f32_e32 v4, 0, v224
	v_add_f32_e32 v4, v226, v4
	v_add_f32_e32 v4, v227, v4
	v_max_f32_e32 v5, v81, v81
	v_max_f32_e32 v6, v80, v80
	v_add_f32_e32 v4, v228, v4
	v_max_f32_e32 v5, v6, v5
	v_add_f32_e32 v4, v229, v4
	v_max3_f32 v5, v5, v82, v83
	v_add_f32_e32 v4, v230, v4
	v_max3_f32 v5, v5, v84, v85
	v_add_f32_e32 v4, v231, v4
	v_max3_f32 v5, v5, v86, v87
	v_add_f32_e32 v4, v232, v4
	v_max3_f32 v5, v5, v88, v89
	v_add_f32_e32 v4, v233, v4
	v_max3_f32 v5, v5, v90, v91
	v_add_f32_e32 v4, v234, v4
	v_max3_f32 v5, v5, v92, v93
	v_add_f32_e32 v4, v235, v4
	v_max3_f32 v5, v5, v94, v95
	v_add_f32_e32 v4, v236, v4
	v_mov_b32_e32 v6, v5
	s_nop 1
	v_permlane32_swap_b32_e32 v6, v5
	s_nop 1
	v_add_f32_e32 v4, v237, v4
	v_add_f32_e32 v4, v222, v4
	v_add_f32_e32 v4, v223, v4
	v_add_f32_e32 v4, v225, v4
	v_add_f32_e32 v8, v208, v4
	s_waitcnt lgkmcnt(0)
	v_max_f32_e32 v4, v6, v6
	v_max_f32_e32 v4, v5, v4
	v_add_f32_e32 v5, 0x41000000, v205
	v_cmp_gt_f32_e32 vcc, v4, v5
	s_cbranch_vccz .LBB0_203
	v_max_f32_e32 v4, v4, v4
	v_max_f32_e32 v5, v205, v205
	v_max_f32_e32 v5, v5, v4
	v_sub_f32_e32 v4, v205, v5
	v_exp_f32_e32 v4, v4
	v_mov_b32_e32 v205, v5
	v_mul_f32_e32 v8, v8, v4
	v_pk_mul_f32 v[46:47], v[46:47], v[4:5] op_sel_hi:[1,0]
	v_pk_mul_f32 v[44:45], v[44:45], v[4:5] op_sel_hi:[1,0]
	v_pk_mul_f32 v[42:43], v[42:43], v[4:5] op_sel_hi:[1,0]
	v_pk_mul_f32 v[40:41], v[40:41], v[4:5] op_sel_hi:[1,0]
	v_pk_mul_f32 v[38:39], v[38:39], v[4:5] op_sel_hi:[1,0]
	v_pk_mul_f32 v[36:37], v[36:37], v[4:5] op_sel_hi:[1,0]
	v_pk_mul_f32 v[34:35], v[34:35], v[4:5] op_sel_hi:[1,0]
	v_pk_mul_f32 v[32:33], v[32:33], v[4:5] op_sel_hi:[1,0]
	v_pk_mul_f32 v[30:31], v[30:31], v[4:5] op_sel_hi:[1,0]
	v_pk_mul_f32 v[28:29], v[28:29], v[4:5] op_sel_hi:[1,0]
	v_pk_mul_f32 v[26:27], v[26:27], v[4:5] op_sel_hi:[1,0]
	v_pk_mul_f32 v[24:25], v[24:25], v[4:5] op_sel_hi:[1,0]
	v_pk_mul_f32 v[22:23], v[22:23], v[4:5] op_sel_hi:[1,0]
	v_pk_mul_f32 v[20:21], v[20:21], v[4:5] op_sel_hi:[1,0]
	v_pk_mul_f32 v[18:19], v[18:19], v[4:5] op_sel_hi:[1,0]
	v_pk_mul_f32 v[16:17], v[16:17], v[4:5] op_sel_hi:[1,0]
	s_branch .LBB0_203
.LBB0_214:
	s_waitcnt vmcnt(0) lgkmcnt(0)
	s_barrier
	v_lshlrev_b32_e32 v8, 1, v209
	v_lshl_add_u32 v14, v218, 1, v8
	ds_read_b128 v[4:7], v14
	v_lshl_add_u32 v15, v217, 1, v8
	v_lshl_add_u32 v162, v216, 1, v8
	v_lshl_add_u32 v163, v215, 1, v8
	v_sub_u32_e32 v215, v8, v209
	v_lshl_add_u32 v164, v214, 1, v215
	v_lshl_add_u32 v13, v213, 1, v215
	s_waitcnt lgkmcnt(0)
	v_mfma_f32_32x32x16_bf16 v[96:111], v[4:7], v[152:155], 0
	v_mfma_f32_32x32x16_bf16 v[80:95], v[4:7], v[156:159], 0
	ds_read_b128 v[4:7], v15
	s_waitcnt lgkmcnt(0)
	v_mfma_f32_32x32x16_bf16 v[96:111], v[4:7], v[140:143], v[96:111]
	v_mfma_f32_32x32x16_bf16 v[80:95], v[4:7], v[148:151], v[80:95]
	ds_read_b128 v[4:7], v162
	s_waitcnt lgkmcnt(0)
	v_mfma_f32_32x32x16_bf16 v[96:111], v[4:7], v[136:139], v[96:111]
	v_mfma_f32_32x32x16_bf16 v[80:95], v[4:7], v[144:147], v[80:95]
	ds_read_b128 v[4:7], v163
	s_waitcnt lgkmcnt(0)
	v_mfma_f32_32x32x16_bf16 v[96:111], v[4:7], v[124:127], v[96:111]
	v_mfma_f32_32x32x16_bf16 v[80:95], v[4:7], v[132:135], v[80:95]
	ds_read_b128 v[4:7], v164 offset:16384
	s_waitcnt lgkmcnt(0)
	v_mfma_f32_32x32x16_bf16 v[96:111], v[4:7], v[120:123], v[96:111]
	v_mfma_f32_32x32x16_bf16 v[80:95], v[4:7], v[128:131], v[80:95]
	ds_read_b128 v[4:7], v13 offset:16384
	s_waitcnt lgkmcnt(0)
	v_mfma_f32_32x32x16_bf16 v[96:111], v[4:7], v[112:115], v[96:111]
	v_mfma_f32_32x32x16_bf16 v[80:95], v[4:7], v[116:119], v[80:95]
	s_nop 10
	v_max_f32_e32 v4, v97, v97
	v_max_f32_e32 v5, v96, v96
	v_max_f32_e32 v4, v5, v4
	v_max3_f32 v4, v4, v98, v99
	v_max3_f32 v4, v4, v100, v101
	v_max3_f32 v4, v4, v102, v103
	v_max3_f32 v4, v4, v104, v105
	v_max3_f32 v4, v4, v106, v107
	v_max3_f32 v4, v4, v108, v109
	v_max3_f32 v4, v4, v110, v111
	v_mov_b32_e32 v5, v4
	s_nop 1
	v_permlane32_swap_b32_e32 v5, v4
	s_nop 1
	s_waitcnt lgkmcnt(0)
	v_max_f32_e32 v5, v5, v5
	v_max_f32_e32 v4, v4, v5
	v_add_f32_e32 v5, 0x41000000, v1
	v_cmp_gt_f32_e32 vcc, v4, v5
	s_cbranch_vccz .LBB0_216
	v_max_f32_e32 v4, v4, v4
	v_max_f32_e32 v5, v1, v1
	v_max_f32_e32 v5, v5, v4
	v_sub_f32_e32 v1, v1, v5
	v_exp_f32_e32 v4, v1
	v_mov_b32_e32 v1, v5
	v_mul_f32_e32 v3, v3, v4
	v_pk_mul_f32 v[78:79], v[78:79], v[4:5] op_sel_hi:[1,0]
	v_pk_mul_f32 v[76:77], v[76:77], v[4:5] op_sel_hi:[1,0]
	v_pk_mul_f32 v[74:75], v[74:75], v[4:5] op_sel_hi:[1,0]
	v_pk_mul_f32 v[72:73], v[72:73], v[4:5] op_sel_hi:[1,0]
	v_pk_mul_f32 v[70:71], v[70:71], v[4:5] op_sel_hi:[1,0]
	v_pk_mul_f32 v[68:69], v[68:69], v[4:5] op_sel_hi:[1,0]
	v_pk_mul_f32 v[66:67], v[66:67], v[4:5] op_sel_hi:[1,0]
	v_pk_mul_f32 v[64:65], v[64:65], v[4:5] op_sel_hi:[1,0]
	v_pk_mul_f32 v[62:63], v[62:63], v[4:5] op_sel_hi:[1,0]
	v_pk_mul_f32 v[60:61], v[60:61], v[4:5] op_sel_hi:[1,0]
	v_pk_mul_f32 v[58:59], v[58:59], v[4:5] op_sel_hi:[1,0]
	v_pk_mul_f32 v[56:57], v[56:57], v[4:5] op_sel_hi:[1,0]
	v_pk_mul_f32 v[54:55], v[54:55], v[4:5] op_sel_hi:[1,0]
	v_pk_mul_f32 v[52:53], v[52:53], v[4:5] op_sel_hi:[1,0]
	v_pk_mul_f32 v[50:51], v[50:51], v[4:5] op_sel_hi:[1,0]
	v_pk_mul_f32 v[48:49], v[48:49], v[4:5] op_sel_hi:[1,0]
.LBB0_216:
	v_max_f32_e32 v4, v81, v81
	v_max_f32_e32 v5, v80, v80
	v_max_f32_e32 v4, v5, v4
	v_max3_f32 v4, v4, v82, v83
	v_max3_f32 v4, v4, v84, v85
	v_max3_f32 v4, v4, v86, v87
	v_max3_f32 v4, v4, v88, v89
	v_max3_f32 v4, v4, v90, v91
	v_max3_f32 v4, v4, v92, v93
	v_max3_f32 v4, v4, v94, v95
	v_mov_b32_e32 v5, v4
	s_nop 1
	v_permlane32_swap_b32_e32 v5, v4
	s_nop 1
	s_waitcnt lgkmcnt(0)
	v_max_f32_e32 v5, v5, v5
	v_max_f32_e32 v4, v4, v5
	v_add_f32_e32 v5, 0x41000000, v205
	v_cmp_gt_f32_e32 vcc, v4, v5
	s_cbranch_vccz .LBB0_218
	v_max_f32_e32 v4, v4, v4
	v_max_f32_e32 v5, v205, v205
	v_max_f32_e32 v5, v5, v4
	v_sub_f32_e32 v4, v205, v5
	v_exp_f32_e32 v4, v4
	v_mov_b32_e32 v205, v5
	v_mul_f32_e32 v208, v208, v4
	v_pk_mul_f32 v[46:47], v[46:47], v[4:5] op_sel_hi:[1,0]
	v_pk_mul_f32 v[44:45], v[44:45], v[4:5] op_sel_hi:[1,0]
	v_pk_mul_f32 v[42:43], v[42:43], v[4:5] op_sel_hi:[1,0]
	v_pk_mul_f32 v[40:41], v[40:41], v[4:5] op_sel_hi:[1,0]
	v_pk_mul_f32 v[38:39], v[38:39], v[4:5] op_sel_hi:[1,0]
	v_pk_mul_f32 v[36:37], v[36:37], v[4:5] op_sel_hi:[1,0]
	v_pk_mul_f32 v[34:35], v[34:35], v[4:5] op_sel_hi:[1,0]
	v_pk_mul_f32 v[32:33], v[32:33], v[4:5] op_sel_hi:[1,0]
	v_pk_mul_f32 v[30:31], v[30:31], v[4:5] op_sel_hi:[1,0]
	v_pk_mul_f32 v[28:29], v[28:29], v[4:5] op_sel_hi:[1,0]
	v_pk_mul_f32 v[26:27], v[26:27], v[4:5] op_sel_hi:[1,0]
	v_pk_mul_f32 v[24:25], v[24:25], v[4:5] op_sel_hi:[1,0]
	v_pk_mul_f32 v[22:23], v[22:23], v[4:5] op_sel_hi:[1,0]
	v_pk_mul_f32 v[20:21], v[20:21], v[4:5] op_sel_hi:[1,0]
	v_pk_mul_f32 v[18:19], v[18:19], v[4:5] op_sel_hi:[1,0]
	v_pk_mul_f32 v[16:17], v[16:17], v[4:5] op_sel_hi:[1,0]
.LBB0_218:
	v_sub_f32_e32 v4, v96, v1
	v_exp_f32_e32 v4, v4
	v_sub_f32_e32 v6, v97, v1
	v_exp_f32_e32 v6, v6
	v_sub_f32_e32 v7, v98, v1
	v_exp_f32_e32 v7, v7
	v_sub_f32_e32 v8, v99, v1
	v_exp_f32_e32 v8, v8
	v_sub_f32_e32 v9, v100, v1
	v_add_f32_e32 v5, 0, v4
	v_exp_f32_e32 v9, v9
	v_sub_f32_e32 v10, v101, v1
	v_add_f32_e32 v5, v6, v5
	v_exp_f32_e32 v10, v10
	v_sub_f32_e32 v11, v102, v1
	v_add_f32_e32 v5, v7, v5
	v_exp_f32_e32 v11, v11
	v_sub_f32_e32 v12, v103, v1
	v_add_f32_e32 v5, v8, v5
	v_exp_f32_e32 v99, v12
	v_sub_f32_e32 v12, v104, v1
	v_add_f32_e32 v5, v9, v5
	v_exp_f32_e32 v100, v12
	v_sub_f32_e32 v12, v105, v1
	v_add_f32_e32 v5, v10, v5
	v_exp_f32_e32 v101, v12
	v_sub_f32_e32 v12, v106, v1
	v_add_f32_e32 v5, v11, v5
	v_exp_f32_e32 v102, v12
	v_sub_f32_e32 v12, v107, v1
	v_add_f32_e32 v5, v99, v5
	v_exp_f32_e32 v103, v12
	v_sub_f32_e32 v12, v108, v1
	v_add_f32_e32 v5, v100, v5
	v_exp_f32_e32 v104, v12
	v_sub_f32_e32 v12, v109, v1
	v_add_f32_e32 v5, v101, v5
	v_exp_f32_e32 v105, v12
	v_sub_f32_e32 v12, v110, v1
	v_add_f32_e32 v5, v102, v5
	v_exp_f32_e32 v106, v12
	v_sub_f32_e32 v12, v111, v1
	v_add_f32_e32 v5, v103, v5
	v_exp_f32_e32 v107, v12
	v_add_f32_e32 v5, v104, v5
	v_add_f32_e32 v5, v105, v5
	v_add_f32_e32 v5, v106, v5
	v_add_f32_e32 v5, v107, v5
	v_add_f32_e32 v12, v3, v5
	v_sub_f32_e32 v3, v80, v205
	v_exp_f32_e32 v167, v3
	v_sub_f32_e32 v3, v81, v205
	v_exp_f32_e32 v213, v3
	v_sub_f32_e32 v3, v82, v205
	v_exp_f32_e32 v214, v3
	v_sub_f32_e32 v3, v83, v205
	v_exp_f32_e32 v216, v3
	v_sub_f32_e32 v3, v84, v205
	v_exp_f32_e32 v217, v3
	v_sub_f32_e32 v3, v85, v205
	v_exp_f32_e32 v218, v3
	v_sub_f32_e32 v3, v86, v205
	v_exp_f32_e32 v219, v3
	v_sub_f32_e32 v3, v87, v205
	v_exp_f32_e32 v220, v3
	v_sub_f32_e32 v3, v88, v205
	v_exp_f32_e32 v221, v3
	v_sub_f32_e32 v3, v89, v205
	v_exp_f32_e32 v222, v3
	v_sub_f32_e32 v3, v90, v205
	v_exp_f32_e32 v223, v3
	v_sub_f32_e32 v3, v91, v205
	v_exp_f32_e32 v224, v3
	v_sub_f32_e32 v3, v92, v205
	v_exp_f32_e32 v225, v3
	v_sub_f32_e32 v3, v93, v205
	v_exp_f32_e32 v165, v3
	v_sub_f32_e32 v3, v94, v205
	v_exp_f32_e32 v166, v3
	v_sub_f32_e32 v3, v95, v205
	v_exp_f32_e32 v212, v3
	v_add3_u32 v3, v215, v209, v160
	v_lshl_add_u32 v84, v211, 1, v3
	v_lshl_add_u32 v88, v210, 1, v3
	ds_read2st64_b64 v[84:87], v84 offset0:16 offset1:24
	ds_read2st64_b64 v[88:91], v88 offset0:16 offset1:24
	v_cvt_pk_bf16_f32 v80, v167, v213
	v_cvt_pk_bf16_f32 v81, v214, v216
	v_cvt_pk_bf16_f32 v82, v217, v218
	s_waitcnt lgkmcnt(0)
	v_mov_b32_e32 v92, v84
	v_mov_b32_e32 v93, v85
	v_mov_b32_e32 v94, v88
	v_mov_b32_e32 v95, v89
	v_mov_b32_e32 v88, v86
	v_mov_b32_e32 v89, v87
	v_cvt_pk_bf16_f32 v83, v219, v220
	v_lshl_add_u32 v84, v206, 1, v3
	ds_read2st64_b64 v[84:87], v84 offset0:16 offset1:24
	v_mfma_f32_32x32x16_bf16 v[32:47], v[92:95], v[80:83], v[32:47]
	v_cvt_pk_bf16_f32 v96, v4, v6
	v_cvt_pk_bf16_f32 v97, v7, v8
	v_cvt_pk_bf16_f32 v98, v9, v10
	v_cvt_pk_bf16_f32 v99, v11, v99
	v_cvt_pk_bf16_f32 v4, v100, v101
	v_cvt_pk_bf16_f32 v5, v102, v103
	v_cvt_pk_bf16_f32 v6, v104, v105
	v_mfma_f32_32x32x16_bf16 v[16:31], v[88:91], v[80:83], v[16:31]
	v_lshl_add_u32 v80, v207, 1, v3
	ds_read2st64_b64 v[80:83], v80 offset0:16 offset1:24
	v_cvt_pk_bf16_f32 v7, v106, v107
	v_cvt_pk_bf16_f32 v8, v221, v222
	v_cvt_pk_bf16_f32 v9, v223, v224
	v_cvt_pk_bf16_f32 v10, v225, v165
	v_cvt_pk_bf16_f32 v11, v166, v212
	v_mfma_f32_32x32x16_bf16 v[64:79], v[92:95], v[96:99], v[64:79]
	v_mfma_f32_32x32x16_bf16 v[48:63], v[88:91], v[96:99], v[48:63]
	s_waitcnt lgkmcnt(0)
	v_mov_b32_e32 v88, v80
	v_mov_b32_e32 v89, v81
	v_mov_b32_e32 v90, v84
	v_mov_b32_e32 v91, v85
	v_mov_b32_e32 v84, v82
	v_mov_b32_e32 v85, v83
	v_mfma_f32_32x32x16_bf16 v[64:79], v[88:91], v[4:7], v[64:79]
	s_nop 0
	v_mfma_f32_32x32x16_bf16 v[48:63], v[84:87], v[4:7], v[48:63]
	ds_read_b128 v[4:7], v14 offset:4096
	v_mfma_f32_32x32x16_bf16 v[32:47], v[88:91], v[8:11], v[32:47]
	v_mfma_f32_32x32x16_bf16 v[16:31], v[84:87], v[8:11], v[16:31]
	s_waitcnt lgkmcnt(0)
	v_mfma_f32_32x32x16_bf16 v[96:111], v[4:7], v[152:155], 0
	v_mfma_f32_32x32x16_bf16 v[80:95], v[4:7], v[156:159], 0
	ds_read_b128 v[4:7], v15 offset:4096
	s_waitcnt lgkmcnt(0)
	v_mfma_f32_32x32x16_bf16 v[96:111], v[4:7], v[140:143], v[96:111]
	v_mfma_f32_32x32x16_bf16 v[80:95], v[4:7], v[148:151], v[80:95]
	ds_read_b128 v[4:7], v162 offset:4096
	s_waitcnt lgkmcnt(0)
	v_mfma_f32_32x32x16_bf16 v[96:111], v[4:7], v[136:139], v[96:111]
	v_mfma_f32_32x32x16_bf16 v[80:95], v[4:7], v[144:147], v[80:95]
	ds_read_b128 v[4:7], v163 offset:4096
	s_waitcnt lgkmcnt(0)
	v_mfma_f32_32x32x16_bf16 v[96:111], v[4:7], v[124:127], v[96:111]
	v_mfma_f32_32x32x16_bf16 v[80:95], v[4:7], v[132:135], v[80:95]
	ds_read_b128 v[4:7], v164 offset:18432
	s_waitcnt lgkmcnt(0)
	v_mfma_f32_32x32x16_bf16 v[96:111], v[4:7], v[120:123], v[96:111]
	v_mfma_f32_32x32x16_bf16 v[80:95], v[4:7], v[128:131], v[80:95]
	ds_read_b128 v[4:7], v13 offset:18432
	s_waitcnt lgkmcnt(0)
	v_mfma_f32_32x32x16_bf16 v[96:111], v[4:7], v[112:115], v[96:111]
	v_mfma_f32_32x32x16_bf16 v[80:95], v[4:7], v[116:119], v[80:95]
	s_nop 10
	v_max_f32_e32 v4, v97, v97
	v_max_f32_e32 v5, v96, v96
	v_max_f32_e32 v4, v5, v4
	v_max3_f32 v4, v4, v98, v99
	v_max3_f32 v4, v4, v100, v101
	v_max3_f32 v4, v4, v102, v103
	v_max3_f32 v4, v4, v104, v105
	v_max3_f32 v4, v4, v106, v107
	v_max3_f32 v4, v4, v108, v109
	v_max3_f32 v4, v4, v110, v111
	v_mov_b32_e32 v5, v4
	s_nop 1
	v_permlane32_swap_b32_e32 v5, v4
	s_nop 1
	s_waitcnt lgkmcnt(0)
	v_max_f32_e32 v5, v5, v5
	v_max_f32_e32 v4, v4, v5
	v_add_f32_e32 v5, 0x41000000, v1
	v_cmp_gt_f32_e32 vcc, v4, v5
	s_cbranch_vccz .LBB0_220
	v_max_f32_e32 v4, v4, v4
	v_max_f32_e32 v5, v1, v1
	v_max_f32_e32 v5, v5, v4
	v_sub_f32_e32 v1, v1, v5
	v_exp_f32_e32 v4, v1
	v_mov_b32_e32 v1, v5
	v_mul_f32_e32 v12, v12, v4
	v_pk_mul_f32 v[78:79], v[78:79], v[4:5] op_sel_hi:[1,0]
	v_pk_mul_f32 v[76:77], v[76:77], v[4:5] op_sel_hi:[1,0]
	v_pk_mul_f32 v[74:75], v[74:75], v[4:5] op_sel_hi:[1,0]
	v_pk_mul_f32 v[72:73], v[72:73], v[4:5] op_sel_hi:[1,0]
	v_pk_mul_f32 v[70:71], v[70:71], v[4:5] op_sel_hi:[1,0]
	v_pk_mul_f32 v[68:69], v[68:69], v[4:5] op_sel_hi:[1,0]
	v_pk_mul_f32 v[66:67], v[66:67], v[4:5] op_sel_hi:[1,0]
	v_pk_mul_f32 v[64:65], v[64:65], v[4:5] op_sel_hi:[1,0]
	v_pk_mul_f32 v[62:63], v[62:63], v[4:5] op_sel_hi:[1,0]
	v_pk_mul_f32 v[60:61], v[60:61], v[4:5] op_sel_hi:[1,0]
	v_pk_mul_f32 v[58:59], v[58:59], v[4:5] op_sel_hi:[1,0]
	v_pk_mul_f32 v[56:57], v[56:57], v[4:5] op_sel_hi:[1,0]
	v_pk_mul_f32 v[54:55], v[54:55], v[4:5] op_sel_hi:[1,0]
	v_pk_mul_f32 v[52:53], v[52:53], v[4:5] op_sel_hi:[1,0]
	v_pk_mul_f32 v[50:51], v[50:51], v[4:5] op_sel_hi:[1,0]
	v_pk_mul_f32 v[48:49], v[48:49], v[4:5] op_sel_hi:[1,0]
.LBB0_220:
	v_add_f32_e32 v4, 0, v167
	v_add_f32_e32 v4, v213, v4
	v_add_f32_e32 v4, v214, v4
	v_max_f32_e32 v5, v81, v81
	v_max_f32_e32 v6, v80, v80
	v_add_f32_e32 v4, v216, v4
	v_max_f32_e32 v5, v6, v5
	v_add_f32_e32 v4, v217, v4
	v_max3_f32 v5, v5, v82, v83
	v_add_f32_e32 v4, v218, v4
	v_max3_f32 v5, v5, v84, v85
	v_add_f32_e32 v4, v219, v4
	v_max3_f32 v5, v5, v86, v87
	v_add_f32_e32 v4, v220, v4
	v_max3_f32 v5, v5, v88, v89
	v_add_f32_e32 v4, v221, v4
	v_max3_f32 v5, v5, v90, v91
	v_add_f32_e32 v4, v222, v4
	v_max3_f32 v5, v5, v92, v93
	v_add_f32_e32 v4, v223, v4
	v_max3_f32 v5, v5, v94, v95
	v_add_f32_e32 v4, v224, v4
	v_mov_b32_e32 v6, v5
	s_nop 1
	v_permlane32_swap_b32_e32 v6, v5
	s_nop 1
	v_add_f32_e32 v4, v225, v4
	v_add_f32_e32 v4, v165, v4
	v_add_f32_e32 v4, v166, v4
	v_add_f32_e32 v4, v212, v4
	v_add_f32_e32 v8, v208, v4
	s_waitcnt lgkmcnt(0)
	v_max_f32_e32 v4, v6, v6
	v_max_f32_e32 v4, v5, v4
	v_add_f32_e32 v5, 0x41000000, v205
	v_cmp_gt_f32_e32 vcc, v4, v5
	s_cbranch_vccz .LBB0_222
	v_max_f32_e32 v4, v4, v4
	v_max_f32_e32 v5, v205, v205
	v_max_f32_e32 v5, v5, v4
	v_sub_f32_e32 v4, v205, v5
	v_exp_f32_e32 v4, v4
	v_mov_b32_e32 v205, v5
	v_mul_f32_e32 v8, v8, v4
	v_pk_mul_f32 v[46:47], v[46:47], v[4:5] op_sel_hi:[1,0]
	v_pk_mul_f32 v[44:45], v[44:45], v[4:5] op_sel_hi:[1,0]
	v_pk_mul_f32 v[42:43], v[42:43], v[4:5] op_sel_hi:[1,0]
	v_pk_mul_f32 v[40:41], v[40:41], v[4:5] op_sel_hi:[1,0]
	v_pk_mul_f32 v[38:39], v[38:39], v[4:5] op_sel_hi:[1,0]
	v_pk_mul_f32 v[36:37], v[36:37], v[4:5] op_sel_hi:[1,0]
	v_pk_mul_f32 v[34:35], v[34:35], v[4:5] op_sel_hi:[1,0]
	v_pk_mul_f32 v[32:33], v[32:33], v[4:5] op_sel_hi:[1,0]
	v_pk_mul_f32 v[30:31], v[30:31], v[4:5] op_sel_hi:[1,0]
	v_pk_mul_f32 v[28:29], v[28:29], v[4:5] op_sel_hi:[1,0]
	v_pk_mul_f32 v[26:27], v[26:27], v[4:5] op_sel_hi:[1,0]
	v_pk_mul_f32 v[24:25], v[24:25], v[4:5] op_sel_hi:[1,0]
	v_pk_mul_f32 v[22:23], v[22:23], v[4:5] op_sel_hi:[1,0]
	v_pk_mul_f32 v[20:21], v[20:21], v[4:5] op_sel_hi:[1,0]
	v_pk_mul_f32 v[18:19], v[18:19], v[4:5] op_sel_hi:[1,0]
	v_pk_mul_f32 v[16:17], v[16:17], v[4:5] op_sel_hi:[1,0]

.LBB0_228:
	v_lshl_or_b32 v204, s41, 14, v165
	v_lshl_add_u32 v13, v203, 1, v204
	ds_read_b128 v[4:7], v13
	v_lshl_add_u32 v14, v202, 1, v204
	v_lshl_add_u32 v15, v201, 1, v204
	v_lshl_add_u32 v12, v167, 1, v204
	v_cmp_lt_i32_e32 vcc, v180, v182
	s_waitcnt lgkmcnt(0)
	v_mfma_f32_32x32x16_bf16 v[96:111], v[4:7], v[136:139], 0
	v_cndmask_b32_e32 v0, v179, v180, vcc
	v_lshlrev_b32_e32 v0, 2, v0
	v_mfma_f32_32x32x16_bf16 v[80:95], v[4:7], v[140:143], 0
	ds_read_b128 v[4:7], v14
	s_waitcnt lgkmcnt(0)
	v_mfma_f32_32x32x16_bf16 v[96:111], v[4:7], v[124:127], v[96:111]
	v_mfma_f32_32x32x16_bf16 v[80:95], v[4:7], v[132:135], v[80:95]
	ds_read_b128 v[4:7], v15
	s_waitcnt lgkmcnt(0)
	v_mfma_f32_32x32x16_bf16 v[96:111], v[4:7], v[120:123], v[96:111]
	v_mfma_f32_32x32x16_bf16 v[80:95], v[4:7], v[128:131], v[80:95]
	ds_read_b128 v[4:7], v12
	s_waitcnt lgkmcnt(0)
	v_mfma_f32_32x32x16_bf16 v[96:111], v[4:7], v[112:115], v[96:111]
	v_mfma_f32_32x32x16_bf16 v[80:95], v[4:7], v[116:119], v[80:95]
	s_nop 10
	v_max_f32_e32 v4, v97, v97
	v_max_f32_e32 v5, v96, v96
	v_max_f32_e32 v4, v5, v4
	v_max3_f32 v4, v4, v98, v99
	v_max3_f32 v4, v4, v100, v101
	v_max3_f32 v4, v4, v102, v103
	v_max3_f32 v4, v4, v104, v105
	v_max3_f32 v4, v4, v106, v107
	v_max3_f32 v4, v4, v108, v109
	v_max3_f32 v4, v4, v110, v111
	v_mov_b32_e32 v5, v4
	s_nop 1
	v_permlane32_swap_b32_e32 v5, v4
	s_nop 1
	s_waitcnt lgkmcnt(0)
	v_max_f32_e32 v5, v5, v5
	v_max_f32_e32 v4, v4, v5
	v_add_f32_e32 v5, 0x41000000, v1
	v_cmp_gt_f32_e32 vcc, v4, v5
	s_cbranch_vccz .LBB0_230
	v_max_f32_e32 v4, v4, v4
	v_max_f32_e32 v5, v1, v1
	v_max_f32_e32 v5, v5, v4
	v_sub_f32_e32 v1, v1, v5
	v_exp_f32_e32 v4, v1
	v_mov_b32_e32 v1, v5
	v_mul_f32_e32 v3, v3, v4
	v_pk_mul_f32 v[78:79], v[78:79], v[4:5] op_sel_hi:[1,0]
	v_pk_mul_f32 v[76:77], v[76:77], v[4:5] op_sel_hi:[1,0]
	v_pk_mul_f32 v[74:75], v[74:75], v[4:5] op_sel_hi:[1,0]
	v_pk_mul_f32 v[72:73], v[72:73], v[4:5] op_sel_hi:[1,0]
	v_pk_mul_f32 v[70:71], v[70:71], v[4:5] op_sel_hi:[1,0]
	v_pk_mul_f32 v[68:69], v[68:69], v[4:5] op_sel_hi:[1,0]
	v_pk_mul_f32 v[66:67], v[66:67], v[4:5] op_sel_hi:[1,0]
	v_pk_mul_f32 v[64:65], v[64:65], v[4:5] op_sel_hi:[1,0]
	v_pk_mul_f32 v[62:63], v[62:63], v[4:5] op_sel_hi:[1,0]
	v_pk_mul_f32 v[60:61], v[60:61], v[4:5] op_sel_hi:[1,0]
	v_pk_mul_f32 v[58:59], v[58:59], v[4:5] op_sel_hi:[1,0]
	v_pk_mul_f32 v[56:57], v[56:57], v[4:5] op_sel_hi:[1,0]
	v_pk_mul_f32 v[54:55], v[54:55], v[4:5] op_sel_hi:[1,0]
	v_pk_mul_f32 v[52:53], v[52:53], v[4:5] op_sel_hi:[1,0]
	v_pk_mul_f32 v[50:51], v[50:51], v[4:5] op_sel_hi:[1,0]
	v_pk_mul_f32 v[48:49], v[48:49], v[4:5] op_sel_hi:[1,0]
.LBB0_230:
	v_max_f32_e32 v4, v81, v81
	v_max_f32_e32 v5, v80, v80
	v_max_f32_e32 v4, v5, v4
	v_max3_f32 v4, v4, v82, v83
	v_max3_f32 v4, v4, v84, v85
	v_max3_f32 v4, v4, v86, v87
	v_max3_f32 v4, v4, v88, v89
	v_max3_f32 v4, v4, v90, v91
	v_max3_f32 v4, v4, v92, v93
	v_max3_f32 v4, v4, v94, v95
	v_mov_b32_e32 v5, v4
	s_nop 1
	v_permlane32_swap_b32_e32 v5, v4
	s_nop 1
	s_waitcnt lgkmcnt(0)
	v_max_f32_e32 v5, v5, v5
	v_max_f32_e32 v4, v4, v5
	v_add_f32_e32 v5, 0x41000000, v159
	v_cmp_gt_f32_e32 vcc, v4, v5
	s_cbranch_vccz .LBB0_232
	v_max_f32_e32 v4, v4, v4
	v_max_f32_e32 v5, v159, v159
	v_max_f32_e32 v5, v5, v4
	v_sub_f32_e32 v4, v159, v5
	v_exp_f32_e32 v4, v4
	v_mov_b32_e32 v159, v5
	v_mul_f32_e32 v162, v162, v4
	v_pk_mul_f32 v[46:47], v[46:47], v[4:5] op_sel_hi:[1,0]
	v_pk_mul_f32 v[44:45], v[44:45], v[4:5] op_sel_hi:[1,0]
	v_pk_mul_f32 v[42:43], v[42:43], v[4:5] op_sel_hi:[1,0]
	v_pk_mul_f32 v[40:41], v[40:41], v[4:5] op_sel_hi:[1,0]
	v_pk_mul_f32 v[38:39], v[38:39], v[4:5] op_sel_hi:[1,0]
	v_pk_mul_f32 v[36:37], v[36:37], v[4:5] op_sel_hi:[1,0]
	v_pk_mul_f32 v[34:35], v[34:35], v[4:5] op_sel_hi:[1,0]
	v_pk_mul_f32 v[32:33], v[32:33], v[4:5] op_sel_hi:[1,0]
	v_pk_mul_f32 v[30:31], v[30:31], v[4:5] op_sel_hi:[1,0]
	v_pk_mul_f32 v[28:29], v[28:29], v[4:5] op_sel_hi:[1,0]
	v_pk_mul_f32 v[26:27], v[26:27], v[4:5] op_sel_hi:[1,0]
	v_pk_mul_f32 v[24:25], v[24:25], v[4:5] op_sel_hi:[1,0]
	v_pk_mul_f32 v[22:23], v[22:23], v[4:5] op_sel_hi:[1,0]
	v_pk_mul_f32 v[20:21], v[20:21], v[4:5] op_sel_hi:[1,0]
	v_pk_mul_f32 v[18:19], v[18:19], v[4:5] op_sel_hi:[1,0]
	v_pk_mul_f32 v[16:17], v[16:17], v[4:5] op_sel_hi:[1,0]
.LBB0_232:
	v_sub_f32_e32 v4, v96, v1
	v_exp_f32_e32 v4, v4
	v_sub_f32_e32 v6, v97, v1
	v_exp_f32_e32 v6, v6
	v_sub_f32_e32 v7, v98, v1
	v_exp_f32_e32 v7, v7
	v_sub_f32_e32 v8, v99, v1
	v_exp_f32_e32 v8, v8
	v_add_f32_e32 v5, 0, v4
	v_add_f32_e32 v5, v6, v5
	v_add_f32_e32 v5, v7, v5
	v_add_f32_e32 v5, v8, v5
	v_cvt_pk_bf16_f32 v97, v7, v8
	v_sub_f32_e32 v8, v80, v159
	v_exp_f32_e32 v207, v8
	v_sub_f32_e32 v8, v81, v159
	v_exp_f32_e32 v209, v8
	v_sub_f32_e32 v8, v82, v159
	v_exp_f32_e32 v210, v8
	v_sub_f32_e32 v8, v83, v159
	v_exp_f32_e32 v211, v8
	v_sub_f32_e32 v8, v84, v159
	v_exp_f32_e32 v212, v8
	v_sub_f32_e32 v8, v85, v159
	v_exp_f32_e32 v213, v8
	v_sub_f32_e32 v8, v86, v159
	v_exp_f32_e32 v214, v8
	v_sub_f32_e32 v8, v87, v159
	v_exp_f32_e32 v215, v8
	v_sub_f32_e32 v8, v88, v159
	v_exp_f32_e32 v216, v8
	v_sub_f32_e32 v8, v89, v159
	v_lshl_add_u32 v204, v154, 1, v204
	v_exp_f32_e32 v217, v8
	v_sub_f32_e32 v8, v90, v159
	v_lshl_add_u32 v84, v164, 1, v204
	v_lshl_add_u32 v88, v163, 1, v204
	v_exp_f32_e32 v218, v8
	v_sub_f32_e32 v8, v91, v159
	ds_read2st64_b64 v[84:87], v84 offset0:16 offset1:24
	ds_read2st64_b64 v[88:91], v88 offset0:16 offset1:24
	v_exp_f32_e32 v219, v8
	v_sub_f32_e32 v8, v92, v159
	v_sub_f32_e32 v9, v100, v1
	v_sub_f32_e32 v96, v103, v1
	v_exp_f32_e32 v220, v8
	v_sub_f32_e32 v8, v93, v159
	v_exp_f32_e32 v9, v9
	v_sub_f32_e32 v10, v101, v1
	v_exp_f32_e32 v99, v96
	v_sub_f32_e32 v96, v104, v1
	v_exp_f32_e32 v205, v8
	v_sub_f32_e32 v8, v94, v159
	v_exp_f32_e32 v10, v10
	v_sub_f32_e32 v11, v102, v1
	v_exp_f32_e32 v100, v96
	v_sub_f32_e32 v96, v105, v1
	v_exp_f32_e32 v206, v8
	v_sub_f32_e32 v8, v95, v159
	s_waitcnt lgkmcnt(0)
	v_mov_b32_e32 v92, v84
	v_mov_b32_e32 v93, v85
	v_mov_b32_e32 v94, v88
	v_mov_b32_e32 v95, v89
	v_mov_b32_e32 v88, v86
	v_mov_b32_e32 v89, v87
	v_exp_f32_e32 v11, v11
	v_exp_f32_e32 v101, v96
	v_sub_f32_e32 v96, v106, v1
	v_exp_f32_e32 v102, v96
	v_sub_f32_e32 v96, v107, v1
	v_add_f32_e32 v5, v9, v5
	v_exp_f32_e32 v103, v96
	v_sub_f32_e32 v96, v108, v1
	v_add_f32_e32 v5, v10, v5
	v_exp_f32_e32 v104, v96
	v_sub_f32_e32 v96, v109, v1
	v_cvt_pk_bf16_f32 v80, v207, v209
	v_cvt_pk_bf16_f32 v81, v210, v211
	v_cvt_pk_bf16_f32 v82, v212, v213
	v_cvt_pk_bf16_f32 v83, v214, v215
	v_add_f32_e32 v5, v11, v5
	v_exp_f32_e32 v105, v96
	v_sub_f32_e32 v96, v110, v1
	v_mfma_f32_32x32x16_bf16 v[32:47], v[92:95], v[80:83], v[32:47]
	v_lshl_add_u32 v84, v160, 1, v204
	v_add_f32_e32 v5, v99, v5
	v_exp_f32_e32 v106, v96
	v_sub_f32_e32 v96, v111, v1
	ds_read2st64_b64 v[84:87], v84 offset0:16 offset1:24
	v_add_f32_e32 v5, v100, v5
	v_exp_f32_e32 v107, v96
	v_mfma_f32_32x32x16_bf16 v[16:31], v[88:91], v[80:83], v[16:31]
	v_lshl_add_u32 v80, v161, 1, v204
	ds_read2st64_b64 v[80:83], v80 offset0:16 offset1:24
	v_cvt_pk_bf16_f32 v96, v4, v6
	v_cvt_pk_bf16_f32 v98, v9, v10
	v_cvt_pk_bf16_f32 v99, v11, v99
	v_add_f32_e32 v5, v101, v5
	v_add_f32_e32 v5, v102, v5
	v_mfma_f32_32x32x16_bf16 v[64:79], v[92:95], v[96:99], v[64:79]
	v_add_f32_e32 v5, v103, v5
	v_add_f32_e32 v5, v104, v5
	v_add_f32_e32 v5, v105, v5
	v_add_f32_e32 v5, v106, v5
	v_add_f32_e32 v5, v107, v5
	v_add_f32_e32 v3, v3, v5
	v_cvt_pk_bf16_f32 v4, v100, v101
	v_mfma_f32_32x32x16_bf16 v[48:63], v[88:91], v[96:99], v[48:63]
	s_waitcnt lgkmcnt(0)
	v_mov_b32_e32 v88, v80
	v_mov_b32_e32 v89, v81
	v_mov_b32_e32 v90, v84
	v_mov_b32_e32 v91, v85
	v_mov_b32_e32 v84, v82
	v_mov_b32_e32 v85, v83
	v_cvt_pk_bf16_f32 v5, v102, v103
	v_cvt_pk_bf16_f32 v6, v104, v105
	v_cvt_pk_bf16_f32 v7, v106, v107
	v_exp_f32_e32 v208, v8
	v_cvt_pk_bf16_f32 v8, v216, v217
	v_mfma_f32_32x32x16_bf16 v[64:79], v[88:91], v[4:7], v[64:79]
	v_cvt_pk_bf16_f32 v9, v218, v219
	v_cvt_pk_bf16_f32 v10, v220, v205
	v_cvt_pk_bf16_f32 v11, v206, v208
	v_mfma_f32_32x32x16_bf16 v[48:63], v[84:87], v[4:7], v[48:63]
	ds_read_b128 v[4:7], v13 offset:4096
	v_mfma_f32_32x32x16_bf16 v[32:47], v[88:91], v[8:11], v[32:47]
	v_mfma_f32_32x32x16_bf16 v[16:31], v[84:87], v[8:11], v[16:31]
	s_waitcnt lgkmcnt(0)
	v_mfma_f32_32x32x16_bf16 v[96:111], v[4:7], v[136:139], 0
	v_mfma_f32_32x32x16_bf16 v[80:95], v[4:7], v[140:143], 0
	ds_read_b128 v[4:7], v14 offset:4096
	s_waitcnt lgkmcnt(0)
	v_mfma_f32_32x32x16_bf16 v[96:111], v[4:7], v[124:127], v[96:111]
	v_mfma_f32_32x32x16_bf16 v[80:95], v[4:7], v[132:135], v[80:95]
	ds_read_b128 v[4:7], v15 offset:4096
	s_waitcnt lgkmcnt(0)
	v_mfma_f32_32x32x16_bf16 v[96:111], v[4:7], v[120:123], v[96:111]
	v_mfma_f32_32x32x16_bf16 v[80:95], v[4:7], v[128:131], v[80:95]
	ds_read_b128 v[4:7], v12 offset:4096
	s_waitcnt lgkmcnt(0)
	v_mfma_f32_32x32x16_bf16 v[96:111], v[4:7], v[112:115], v[96:111]
	v_mfma_f32_32x32x16_bf16 v[80:95], v[4:7], v[116:119], v[80:95]
	s_nop 10
	v_max_f32_e32 v4, v97, v97
	v_max_f32_e32 v5, v96, v96
	v_max_f32_e32 v4, v5, v4
	v_max3_f32 v4, v4, v98, v99
	v_max3_f32 v4, v4, v100, v101
	v_max3_f32 v4, v4, v102, v103
	v_max3_f32 v4, v4, v104, v105
	v_max3_f32 v4, v4, v106, v107
	v_max3_f32 v4, v4, v108, v109
	v_max3_f32 v4, v4, v110, v111
	v_mov_b32_e32 v5, v4
	s_nop 1
	v_permlane32_swap_b32_e32 v5, v4
	s_nop 1
	s_waitcnt lgkmcnt(0)
	v_max_f32_e32 v5, v5, v5
	v_max_f32_e32 v4, v4, v5
	v_add_f32_e32 v5, 0x41000000, v1
	v_cmp_gt_f32_e32 vcc, v4, v5
	s_cbranch_vccz .LBB0_234
	v_max_f32_e32 v4, v4, v4
	v_max_f32_e32 v5, v1, v1
	v_max_f32_e32 v5, v5, v4
	v_sub_f32_e32 v1, v1, v5
	v_exp_f32_e32 v4, v1
	v_mov_b32_e32 v1, v5
	v_mul_f32_e32 v3, v3, v4
	v_pk_mul_f32 v[78:79], v[78:79], v[4:5] op_sel_hi:[1,0]
	v_pk_mul_f32 v[76:77], v[76:77], v[4:5] op_sel_hi:[1,0]
	v_pk_mul_f32 v[74:75], v[74:75], v[4:5] op_sel_hi:[1,0]
	v_pk_mul_f32 v[72:73], v[72:73], v[4:5] op_sel_hi:[1,0]
	v_pk_mul_f32 v[70:71], v[70:71], v[4:5] op_sel_hi:[1,0]
	v_pk_mul_f32 v[68:69], v[68:69], v[4:5] op_sel_hi:[1,0]
	v_pk_mul_f32 v[66:67], v[66:67], v[4:5] op_sel_hi:[1,0]
	v_pk_mul_f32 v[64:65], v[64:65], v[4:5] op_sel_hi:[1,0]
	v_pk_mul_f32 v[62:63], v[62:63], v[4:5] op_sel_hi:[1,0]
	v_pk_mul_f32 v[60:61], v[60:61], v[4:5] op_sel_hi:[1,0]
	v_pk_mul_f32 v[58:59], v[58:59], v[4:5] op_sel_hi:[1,0]
	v_pk_mul_f32 v[56:57], v[56:57], v[4:5] op_sel_hi:[1,0]
	v_pk_mul_f32 v[54:55], v[54:55], v[4:5] op_sel_hi:[1,0]
	v_pk_mul_f32 v[52:53], v[52:53], v[4:5] op_sel_hi:[1,0]
	v_pk_mul_f32 v[50:51], v[50:51], v[4:5] op_sel_hi:[1,0]
	v_pk_mul_f32 v[48:49], v[48:49], v[4:5] op_sel_hi:[1,0]
.LBB0_234:
	v_add_f32_e32 v4, 0, v207
	v_add_f32_e32 v4, v209, v4
	v_add_f32_e32 v4, v210, v4
	v_max_f32_e32 v5, v81, v81
	v_max_f32_e32 v6, v80, v80
	v_add_f32_e32 v4, v211, v4
	v_max_f32_e32 v5, v6, v5
	v_add_f32_e32 v4, v212, v4
	v_max3_f32 v5, v5, v82, v83
	v_add_f32_e32 v4, v213, v4
	v_max3_f32 v5, v5, v84, v85
	v_add_f32_e32 v4, v214, v4
	v_max3_f32 v5, v5, v86, v87
	v_add_f32_e32 v4, v215, v4
	v_max3_f32 v5, v5, v88, v89
	v_add_f32_e32 v4, v216, v4
	v_max3_f32 v5, v5, v90, v91
	v_add_f32_e32 v4, v217, v4
	v_max3_f32 v5, v5, v92, v93
	v_add_f32_e32 v4, v218, v4
	v_max3_f32 v5, v5, v94, v95
	v_add_f32_e32 v4, v219, v4
	v_mov_b32_e32 v6, v5
	s_nop 1
	v_permlane32_swap_b32_e32 v6, v5
	s_nop 1
	v_add_f32_e32 v4, v220, v4
	v_add_f32_e32 v4, v205, v4
	v_add_f32_e32 v4, v206, v4
	v_add_f32_e32 v4, v208, v4
	v_add_f32_e32 v8, v162, v4
	s_waitcnt lgkmcnt(0)
	v_max_f32_e32 v4, v6, v6
	v_max_f32_e32 v4, v5, v4
	v_add_f32_e32 v5, 0x41000000, v159
	v_cmp_gt_f32_e32 vcc, v4, v5
	s_cbranch_vccz .LBB0_225
	v_max_f32_e32 v4, v4, v4
	v_max_f32_e32 v5, v159, v159
	v_max_f32_e32 v5, v5, v4
	v_sub_f32_e32 v4, v159, v5
	v_exp_f32_e32 v4, v4
	v_mov_b32_e32 v159, v5
	v_mul_f32_e32 v8, v8, v4
	v_pk_mul_f32 v[46:47], v[46:47], v[4:5] op_sel_hi:[1,0]
	v_pk_mul_f32 v[44:45], v[44:45], v[4:5] op_sel_hi:[1,0]
	v_pk_mul_f32 v[42:43], v[42:43], v[4:5] op_sel_hi:[1,0]
	v_pk_mul_f32 v[40:41], v[40:41], v[4:5] op_sel_hi:[1,0]
	v_pk_mul_f32 v[38:39], v[38:39], v[4:5] op_sel_hi:[1,0]
	v_pk_mul_f32 v[36:37], v[36:37], v[4:5] op_sel_hi:[1,0]
	v_pk_mul_f32 v[34:35], v[34:35], v[4:5] op_sel_hi:[1,0]
	v_pk_mul_f32 v[32:33], v[32:33], v[4:5] op_sel_hi:[1,0]
	v_pk_mul_f32 v[30:31], v[30:31], v[4:5] op_sel_hi:[1,0]
	v_pk_mul_f32 v[28:29], v[28:29], v[4:5] op_sel_hi:[1,0]
	v_pk_mul_f32 v[26:27], v[26:27], v[4:5] op_sel_hi:[1,0]
	v_pk_mul_f32 v[24:25], v[24:25], v[4:5] op_sel_hi:[1,0]
	v_pk_mul_f32 v[22:23], v[22:23], v[4:5] op_sel_hi:[1,0]
	v_pk_mul_f32 v[20:21], v[20:21], v[4:5] op_sel_hi:[1,0]
	v_pk_mul_f32 v[18:19], v[18:19], v[4:5] op_sel_hi:[1,0]
	v_pk_mul_f32 v[16:17], v[16:17], v[4:5] op_sel_hi:[1,0]
	s_branch .LBB0_225
.LBB0_236:
	s_waitcnt vmcnt(0) lgkmcnt(0)
	s_barrier
	v_lshl_add_u32 v14, v203, 1, v165
	ds_read_b128 v[4:7], v14
	v_lshl_add_u32 v15, v202, 1, v165
	v_lshl_add_u32 v148, v201, 1, v165
	v_lshl_add_u32 v13, v167, 1, v165
	s_waitcnt lgkmcnt(0)
	v_mfma_f32_32x32x16_bf16 v[96:111], v[4:7], v[136:139], 0
	v_mfma_f32_32x32x16_bf16 v[80:95], v[4:7], v[140:143], 0
	ds_read_b128 v[4:7], v15
	s_waitcnt lgkmcnt(0)
	v_mfma_f32_32x32x16_bf16 v[96:111], v[4:7], v[124:127], v[96:111]
	v_mfma_f32_32x32x16_bf16 v[80:95], v[4:7], v[132:135], v[80:95]
	ds_read_b128 v[4:7], v148
	s_waitcnt lgkmcnt(0)
	v_mfma_f32_32x32x16_bf16 v[96:111], v[4:7], v[120:123], v[96:111]
	v_mfma_f32_32x32x16_bf16 v[80:95], v[4:7], v[128:131], v[80:95]
	ds_read_b128 v[4:7], v13
	s_waitcnt lgkmcnt(0)
	v_mfma_f32_32x32x16_bf16 v[96:111], v[4:7], v[112:115], v[96:111]
	v_mfma_f32_32x32x16_bf16 v[80:95], v[4:7], v[116:119], v[80:95]
	s_nop 10
	v_max_f32_e32 v4, v97, v97
	v_max_f32_e32 v5, v96, v96
	v_max_f32_e32 v4, v5, v4
	v_max3_f32 v4, v4, v98, v99
	v_max3_f32 v4, v4, v100, v101
	v_max3_f32 v4, v4, v102, v103
	v_max3_f32 v4, v4, v104, v105
	v_max3_f32 v4, v4, v106, v107
	v_max3_f32 v4, v4, v108, v109
	v_max3_f32 v4, v4, v110, v111
	v_mov_b32_e32 v5, v4
	s_nop 1
	v_permlane32_swap_b32_e32 v5, v4
	s_nop 1
	s_waitcnt lgkmcnt(0)
	v_max_f32_e32 v5, v5, v5
	v_max_f32_e32 v4, v4, v5
	v_add_f32_e32 v5, 0x41000000, v1
	v_cmp_gt_f32_e32 vcc, v4, v5
	s_cbranch_vccz .LBB0_238
	v_max_f32_e32 v4, v4, v4
	v_max_f32_e32 v5, v1, v1
	v_max_f32_e32 v5, v5, v4
	v_sub_f32_e32 v1, v1, v5
	v_exp_f32_e32 v4, v1
	v_mov_b32_e32 v1, v5
	v_mul_f32_e32 v3, v3, v4
	v_pk_mul_f32 v[78:79], v[78:79], v[4:5] op_sel_hi:[1,0]
	v_pk_mul_f32 v[76:77], v[76:77], v[4:5] op_sel_hi:[1,0]
	v_pk_mul_f32 v[74:75], v[74:75], v[4:5] op_sel_hi:[1,0]
	v_pk_mul_f32 v[72:73], v[72:73], v[4:5] op_sel_hi:[1,0]
	v_pk_mul_f32 v[70:71], v[70:71], v[4:5] op_sel_hi:[1,0]
	v_pk_mul_f32 v[68:69], v[68:69], v[4:5] op_sel_hi:[1,0]
	v_pk_mul_f32 v[66:67], v[66:67], v[4:5] op_sel_hi:[1,0]
	v_pk_mul_f32 v[64:65], v[64:65], v[4:5] op_sel_hi:[1,0]
	v_pk_mul_f32 v[62:63], v[62:63], v[4:5] op_sel_hi:[1,0]
	v_pk_mul_f32 v[60:61], v[60:61], v[4:5] op_sel_hi:[1,0]
	v_pk_mul_f32 v[58:59], v[58:59], v[4:5] op_sel_hi:[1,0]
	v_pk_mul_f32 v[56:57], v[56:57], v[4:5] op_sel_hi:[1,0]
	v_pk_mul_f32 v[54:55], v[54:55], v[4:5] op_sel_hi:[1,0]
	v_pk_mul_f32 v[52:53], v[52:53], v[4:5] op_sel_hi:[1,0]
	v_pk_mul_f32 v[50:51], v[50:51], v[4:5] op_sel_hi:[1,0]
	v_pk_mul_f32 v[48:49], v[48:49], v[4:5] op_sel_hi:[1,0]

.LBB0_240:
	v_sub_f32_e32 v4, v96, v1
	v_exp_f32_e32 v4, v4
	v_sub_f32_e32 v6, v97, v1
	v_exp_f32_e32 v6, v6
	v_sub_f32_e32 v7, v98, v1
	v_exp_f32_e32 v7, v7
	v_sub_f32_e32 v8, v99, v1
	v_exp_f32_e32 v8, v8
	v_sub_f32_e32 v9, v100, v1
	v_add_f32_e32 v5, 0, v4
	v_exp_f32_e32 v9, v9
	v_sub_f32_e32 v10, v101, v1
	v_add_f32_e32 v5, v6, v5
	v_exp_f32_e32 v10, v10
	v_sub_f32_e32 v11, v102, v1
	v_add_f32_e32 v5, v7, v5
	v_exp_f32_e32 v11, v11
	v_sub_f32_e32 v12, v103, v1
	v_add_f32_e32 v5, v8, v5
	v_exp_f32_e32 v99, v12
	v_sub_f32_e32 v12, v104, v1
	v_add_f32_e32 v5, v9, v5
	v_exp_f32_e32 v100, v12
	v_sub_f32_e32 v12, v105, v1
	v_add_f32_e32 v5, v10, v5
	v_exp_f32_e32 v101, v12
	v_sub_f32_e32 v12, v106, v1
	v_add_f32_e32 v5, v11, v5
	v_exp_f32_e32 v102, v12
	v_sub_f32_e32 v12, v107, v1
	v_add_f32_e32 v5, v99, v5
	v_exp_f32_e32 v103, v12
	v_sub_f32_e32 v12, v108, v1
	v_add_f32_e32 v5, v100, v5
	v_exp_f32_e32 v104, v12
	v_sub_f32_e32 v12, v109, v1
	v_add_f32_e32 v5, v101, v5
	v_exp_f32_e32 v105, v12
	v_sub_f32_e32 v12, v110, v1
	v_add_f32_e32 v5, v102, v5
	v_exp_f32_e32 v106, v12
	v_sub_f32_e32 v12, v111, v1
	v_add_f32_e32 v5, v103, v5
	v_exp_f32_e32 v107, v12
	v_add_f32_e32 v5, v104, v5
	v_add_f32_e32 v5, v105, v5
	v_add_f32_e32 v5, v106, v5
	v_add_f32_e32 v5, v107, v5
	v_add_f32_e32 v12, v3, v5
	v_sub_f32_e32 v3, v80, v159
	v_exp_f32_e32 v151, v3
	v_sub_f32_e32 v3, v81, v159
	v_exp_f32_e32 v153, v3
	v_sub_f32_e32 v3, v82, v159
	v_exp_f32_e32 v166, v3
	v_sub_f32_e32 v3, v83, v159
	v_exp_f32_e32 v167, v3
	v_sub_f32_e32 v3, v84, v159
	v_exp_f32_e32 v201, v3
	v_sub_f32_e32 v3, v85, v159
	v_exp_f32_e32 v202, v3
	v_sub_f32_e32 v3, v86, v159
	v_exp_f32_e32 v203, v3
	v_sub_f32_e32 v3, v87, v159
	v_exp_f32_e32 v204, v3
	v_sub_f32_e32 v3, v88, v159
	v_exp_f32_e32 v205, v3
	v_sub_f32_e32 v3, v89, v159
	v_exp_f32_e32 v206, v3
	v_sub_f32_e32 v3, v90, v159
	v_exp_f32_e32 v207, v3
	v_sub_f32_e32 v3, v91, v159
	v_exp_f32_e32 v208, v3
	v_sub_f32_e32 v3, v92, v159
	v_exp_f32_e32 v209, v3
	v_sub_f32_e32 v3, v93, v159
	v_exp_f32_e32 v149, v3
	v_sub_f32_e32 v3, v94, v159
	v_exp_f32_e32 v150, v3
	v_sub_f32_e32 v3, v95, v159
	v_exp_f32_e32 v152, v3
	v_lshl_add_u32 v3, v154, 1, v165
	v_lshl_add_u32 v84, v164, 1, v3
	v_lshl_add_u32 v88, v163, 1, v3
	ds_read2st64_b64 v[84:87], v84 offset0:16 offset1:24
	ds_read2st64_b64 v[88:91], v88 offset0:16 offset1:24
	v_cvt_pk_bf16_f32 v80, v151, v153
	v_cvt_pk_bf16_f32 v81, v166, v167
	v_cvt_pk_bf16_f32 v82, v201, v202
	s_waitcnt lgkmcnt(0)
	v_mov_b32_e32 v92, v84
	v_mov_b32_e32 v93, v85
	v_mov_b32_e32 v94, v88
	v_mov_b32_e32 v95, v89
	v_mov_b32_e32 v88, v86
	v_mov_b32_e32 v89, v87
	v_cvt_pk_bf16_f32 v83, v203, v204
	v_lshl_add_u32 v84, v160, 1, v3
	ds_read2st64_b64 v[84:87], v84 offset0:16 offset1:24
	v_mfma_f32_32x32x16_bf16 v[32:47], v[92:95], v[80:83], v[32:47]
	v_cvt_pk_bf16_f32 v96, v4, v6
	v_cvt_pk_bf16_f32 v97, v7, v8
	v_cvt_pk_bf16_f32 v98, v9, v10
	v_cvt_pk_bf16_f32 v99, v11, v99
	v_cvt_pk_bf16_f32 v4, v100, v101
	v_cvt_pk_bf16_f32 v5, v102, v103
	v_cvt_pk_bf16_f32 v6, v104, v105
	v_mfma_f32_32x32x16_bf16 v[16:31], v[88:91], v[80:83], v[16:31]
	v_lshl_add_u32 v80, v161, 1, v3
	ds_read2st64_b64 v[80:83], v80 offset0:16 offset1:24
	v_cvt_pk_bf16_f32 v7, v106, v107
	v_cvt_pk_bf16_f32 v8, v205, v206
	v_cvt_pk_bf16_f32 v9, v207, v208
	v_cvt_pk_bf16_f32 v10, v209, v149
	v_cvt_pk_bf16_f32 v11, v150, v152
	v_mfma_f32_32x32x16_bf16 v[64:79], v[92:95], v[96:99], v[64:79]
	v_mfma_f32_32x32x16_bf16 v[48:63], v[88:91], v[96:99], v[48:63]
	s_waitcnt lgkmcnt(0)
	v_mov_b32_e32 v88, v80
	v_mov_b32_e32 v89, v81
	v_mov_b32_e32 v90, v84
	v_mov_b32_e32 v91, v85
	v_mov_b32_e32 v84, v82
	v_mov_b32_e32 v85, v83
	v_mfma_f32_32x32x16_bf16 v[64:79], v[88:91], v[4:7], v[64:79]
	s_nop 0
	v_mfma_f32_32x32x16_bf16 v[48:63], v[84:87], v[4:7], v[48:63]
	ds_read_b128 v[4:7], v14 offset:4096
	v_mfma_f32_32x32x16_bf16 v[32:47], v[88:91], v[8:11], v[32:47]
	v_mfma_f32_32x32x16_bf16 v[16:31], v[84:87], v[8:11], v[16:31]
	s_waitcnt lgkmcnt(0)
	v_mfma_f32_32x32x16_bf16 v[96:111], v[4:7], v[136:139], 0
	v_mfma_f32_32x32x16_bf16 v[80:95], v[4:7], v[140:143], 0
	ds_read_b128 v[4:7], v15 offset:4096
	s_waitcnt lgkmcnt(0)
	v_mfma_f32_32x32x16_bf16 v[96:111], v[4:7], v[124:127], v[96:111]
	v_mfma_f32_32x32x16_bf16 v[80:95], v[4:7], v[132:135], v[80:95]
	ds_read_b128 v[4:7], v148 offset:4096
	s_waitcnt lgkmcnt(0)
	v_mfma_f32_32x32x16_bf16 v[96:111], v[4:7], v[120:123], v[96:111]
	v_mfma_f32_32x32x16_bf16 v[80:95], v[4:7], v[128:131], v[80:95]
	ds_read_b128 v[4:7], v13 offset:4096
	s_waitcnt lgkmcnt(0)
	v_mfma_f32_32x32x16_bf16 v[96:111], v[4:7], v[112:115], v[96:111]
	v_mfma_f32_32x32x16_bf16 v[80:95], v[4:7], v[116:119], v[80:95]
	s_nop 10
	v_max_f32_e32 v4, v97, v97
	v_max_f32_e32 v5, v96, v96
	v_max_f32_e32 v4, v5, v4
	v_max3_f32 v4, v4, v98, v99
	v_max3_f32 v4, v4, v100, v101
	v_max3_f32 v4, v4, v102, v103
	v_max3_f32 v4, v4, v104, v105
	v_max3_f32 v4, v4, v106, v107
	v_max3_f32 v4, v4, v108, v109
	v_max3_f32 v4, v4, v110, v111
	v_mov_b32_e32 v5, v4
	s_nop 1
	v_permlane32_swap_b32_e32 v5, v4
	s_nop 1
	s_waitcnt lgkmcnt(0)
	v_max_f32_e32 v5, v5, v5
	v_max_f32_e32 v4, v4, v5
	v_add_f32_e32 v5, 0x41000000, v1
	v_cmp_gt_f32_e32 vcc, v4, v5
	s_cbranch_vccz .LBB0_242
	v_max_f32_e32 v4, v4, v4
	v_max_f32_e32 v5, v1, v1
	v_max_f32_e32 v5, v5, v4
	v_sub_f32_e32 v1, v1, v5
	v_exp_f32_e32 v4, v1
	v_mov_b32_e32 v1, v5
	v_mul_f32_e32 v12, v12, v4
	v_pk_mul_f32 v[78:79], v[78:79], v[4:5] op_sel_hi:[1,0]
	v_pk_mul_f32 v[76:77], v[76:77], v[4:5] op_sel_hi:[1,0]
	v_pk_mul_f32 v[74:75], v[74:75], v[4:5] op_sel_hi:[1,0]
	v_pk_mul_f32 v[72:73], v[72:73], v[4:5] op_sel_hi:[1,0]
	v_pk_mul_f32 v[70:71], v[70:71], v[4:5] op_sel_hi:[1,0]
	v_pk_mul_f32 v[68:69], v[68:69], v[4:5] op_sel_hi:[1,0]
	v_pk_mul_f32 v[66:67], v[66:67], v[4:5] op_sel_hi:[1,0]
	v_pk_mul_f32 v[64:65], v[64:65], v[4:5] op_sel_hi:[1,0]
	v_pk_mul_f32 v[62:63], v[62:63], v[4:5] op_sel_hi:[1,0]
	v_pk_mul_f32 v[60:61], v[60:61], v[4:5] op_sel_hi:[1,0]
	v_pk_mul_f32 v[58:59], v[58:59], v[4:5] op_sel_hi:[1,0]
	v_pk_mul_f32 v[56:57], v[56:57], v[4:5] op_sel_hi:[1,0]
	v_pk_mul_f32 v[54:55], v[54:55], v[4:5] op_sel_hi:[1,0]
	v_pk_mul_f32 v[52:53], v[52:53], v[4:5] op_sel_hi:[1,0]
	v_pk_mul_f32 v[50:51], v[50:51], v[4:5] op_sel_hi:[1,0]
	v_pk_mul_f32 v[48:49], v[48:49], v[4:5] op_sel_hi:[1,0]
.LBB0_242:
	v_add_f32_e32 v4, 0, v151
	v_add_f32_e32 v4, v153, v4
	v_add_f32_e32 v4, v166, v4
	v_max_f32_e32 v5, v81, v81
	v_max_f32_e32 v6, v80, v80
	v_add_f32_e32 v4, v167, v4
	v_max_f32_e32 v5, v6, v5
	v_add_f32_e32 v4, v201, v4
	v_max3_f32 v5, v5, v82, v83
	v_add_f32_e32 v4, v202, v4
	v_max3_f32 v5, v5, v84, v85
	v_add_f32_e32 v4, v203, v4
	v_max3_f32 v5, v5, v86, v87
	v_add_f32_e32 v4, v204, v4
	v_max3_f32 v5, v5, v88, v89
	v_add_f32_e32 v4, v205, v4
	v_max3_f32 v5, v5, v90, v91
	v_add_f32_e32 v4, v206, v4
	v_max3_f32 v5, v5, v92, v93
	v_add_f32_e32 v4, v207, v4
	v_max3_f32 v5, v5, v94, v95
	v_add_f32_e32 v4, v208, v4
	v_mov_b32_e32 v6, v5
	s_nop 1
	v_permlane32_swap_b32_e32 v6, v5
	s_nop 1
	v_add_f32_e32 v4, v209, v4
	v_add_f32_e32 v4, v149, v4
	v_add_f32_e32 v4, v150, v4
	v_add_f32_e32 v4, v152, v4
	v_add_f32_e32 v8, v162, v4
	s_waitcnt lgkmcnt(0)
	v_max_f32_e32 v4, v6, v6
	v_max_f32_e32 v4, v5, v4
	v_add_f32_e32 v5, 0x41000000, v159
	v_cmp_gt_f32_e32 vcc, v4, v5
	s_cbranch_vccz .LBB0_244
	v_max_f32_e32 v4, v4, v4
	v_max_f32_e32 v5, v159, v159
	v_max_f32_e32 v5, v5, v4
	v_sub_f32_e32 v4, v159, v5
	v_exp_f32_e32 v4, v4
	v_mov_b32_e32 v159, v5
	v_mul_f32_e32 v8, v8, v4
	v_pk_mul_f32 v[46:47], v[46:47], v[4:5] op_sel_hi:[1,0]
	v_pk_mul_f32 v[44:45], v[44:45], v[4:5] op_sel_hi:[1,0]
	v_pk_mul_f32 v[42:43], v[42:43], v[4:5] op_sel_hi:[1,0]
	v_pk_mul_f32 v[40:41], v[40:41], v[4:5] op_sel_hi:[1,0]
	v_pk_mul_f32 v[38:39], v[38:39], v[4:5] op_sel_hi:[1,0]
	v_pk_mul_f32 v[36:37], v[36:37], v[4:5] op_sel_hi:[1,0]
	v_pk_mul_f32 v[34:35], v[34:35], v[4:5] op_sel_hi:[1,0]
	v_pk_mul_f32 v[32:33], v[32:33], v[4:5] op_sel_hi:[1,0]
	v_pk_mul_f32 v[30:31], v[30:31], v[4:5] op_sel_hi:[1,0]
	v_pk_mul_f32 v[28:29], v[28:29], v[4:5] op_sel_hi:[1,0]
	v_pk_mul_f32 v[26:27], v[26:27], v[4:5] op_sel_hi:[1,0]
	v_pk_mul_f32 v[24:25], v[24:25], v[4:5] op_sel_hi:[1,0]
	v_pk_mul_f32 v[22:23], v[22:23], v[4:5] op_sel_hi:[1,0]
	v_pk_mul_f32 v[20:21], v[20:21], v[4:5] op_sel_hi:[1,0]
	v_pk_mul_f32 v[18:19], v[18:19], v[4:5] op_sel_hi:[1,0]
	v_pk_mul_f32 v[16:17], v[16:17], v[4:5] op_sel_hi:[1,0]

.LBB0_274:
	s_mul_i32 s2, s40, 0x5000
	v_lshl_or_b32 v0, v209, 1, s2
	v_lshl_add_u32 v220, v218, 1, v0
	ds_read_b128 v[4:7], v220
	v_lshl_add_u32 v14, v217, 1, v0
	ds_read_b128 v[8:11], v14
	v_lshl_add_u32 v221, v216, 1, v0
	v_lshl_add_u32 v13, v215, 1, v0
	v_or_b32_e32 v219, s2, v209
	v_lshl_add_u32 v15, v214, 1, v219
	v_lshl_add_u32 v12, v213, 1, v219
	v_cmp_lt_i32_e32 vcc, v180, v182
	s_waitcnt lgkmcnt(0)
	v_mfma_f32_32x32x16_bf16 v[96:111], v[4:7], v[152:155], 0
	ds_read_b128 v[222:225], v12 offset:16384
	v_cndmask_b32_e32 v0, v179, v180, vcc
	v_lshlrev_b32_e32 v0, 2, v0
	v_mfma_f32_32x32x16_bf16 v[80:95], v[4:7], v[156:159], 0
	ds_read_b128 v[4:7], v221
	v_mfma_f32_32x32x16_bf16 v[96:111], v[8:11], v[140:143], v[96:111]
	v_mfma_f32_32x32x16_bf16 v[80:95], v[8:11], v[148:151], v[80:95]
	ds_read_b128 v[8:11], v13
	s_waitcnt lgkmcnt(0)
	v_mfma_f32_32x32x16_bf16 v[96:111], v[4:7], v[136:139], v[96:111]
	v_mfma_f32_32x32x16_bf16 v[80:95], v[4:7], v[144:147], v[80:95]
	ds_read_b128 v[4:7], v15 offset:16384
	v_mfma_f32_32x32x16_bf16 v[96:111], v[8:11], v[124:127], v[96:111]
	s_waitcnt lgkmcnt(0)
	v_mfma_f32_32x32x16_bf16 v[96:111], v[4:7], v[120:123], v[96:111]
	v_mfma_f32_32x32x16_bf16 v[96:111], v[222:225], v[112:115], v[96:111]
	v_mfma_f32_32x32x16_bf16 v[80:95], v[8:11], v[132:135], v[80:95]
	s_nop 10
	v_max_f32_e32 v188, v97, v97
	v_max_f32_e32 v8, v96, v96
	v_max_f32_e32 v8, v8, v188
	v_max3_f32 v8, v8, v98, v99
	v_max3_f32 v8, v8, v100, v101
	v_max3_f32 v8, v8, v102, v103
	v_max3_f32 v8, v8, v104, v105
	v_mfma_f32_32x32x16_bf16 v[80:95], v[4:7], v[128:131], v[80:95]
	v_max3_f32 v8, v8, v106, v107
	v_max3_f32 v4, v8, v108, v109
	v_max3_f32 v4, v4, v110, v111
	v_mov_b32_e32 v5, v4
	s_nop 1
	v_permlane32_swap_b32_e32 v5, v4
	s_nop 1
	s_waitcnt lgkmcnt(0)
	v_max_f32_e32 v5, v5, v5
	v_mfma_f32_32x32x16_bf16 v[80:95], v[222:225], v[116:119], v[80:95]
	v_max_f32_e32 v4, v4, v5
	v_add_f32_e32 v5, 0x41000000, v1
	v_cmp_gt_f32_e32 vcc, v4, v5
	s_cbranch_vccz .LBB0_276
	v_max_f32_e32 v4, v4, v4
	v_max_f32_e32 v5, v1, v1
	v_max_f32_e32 v5, v5, v4
	v_sub_f32_e32 v1, v1, v5
	v_exp_f32_e32 v4, v1
	v_mov_b32_e32 v1, v5
	v_mul_f32_e32 v3, v3, v4
	v_pk_mul_f32 v[78:79], v[78:79], v[4:5] op_sel_hi:[1,0]
	v_pk_mul_f32 v[76:77], v[76:77], v[4:5] op_sel_hi:[1,0]
	v_pk_mul_f32 v[74:75], v[74:75], v[4:5] op_sel_hi:[1,0]
	v_pk_mul_f32 v[72:73], v[72:73], v[4:5] op_sel_hi:[1,0]
	v_pk_mul_f32 v[70:71], v[70:71], v[4:5] op_sel_hi:[1,0]
	v_pk_mul_f32 v[68:69], v[68:69], v[4:5] op_sel_hi:[1,0]
	v_pk_mul_f32 v[66:67], v[66:67], v[4:5] op_sel_hi:[1,0]
	v_pk_mul_f32 v[64:65], v[64:65], v[4:5] op_sel_hi:[1,0]
	v_pk_mul_f32 v[62:63], v[62:63], v[4:5] op_sel_hi:[1,0]
	v_pk_mul_f32 v[60:61], v[60:61], v[4:5] op_sel_hi:[1,0]
	v_pk_mul_f32 v[58:59], v[58:59], v[4:5] op_sel_hi:[1,0]
	v_pk_mul_f32 v[56:57], v[56:57], v[4:5] op_sel_hi:[1,0]
	v_pk_mul_f32 v[54:55], v[54:55], v[4:5] op_sel_hi:[1,0]
	v_pk_mul_f32 v[52:53], v[52:53], v[4:5] op_sel_hi:[1,0]
	v_pk_mul_f32 v[50:51], v[50:51], v[4:5] op_sel_hi:[1,0]
	v_pk_mul_f32 v[48:49], v[48:49], v[4:5] op_sel_hi:[1,0]
